# v34 + MLA loop trims (K offset folded into base address once per job, redundant max canonicalisation and zero-init packed adds removed)
# speedup vs baseline: 1.0008x; 1.0008x over previous
; DI int get_tid() { int t = threadIdx.x; asm volatile("" : "+v"(t)); return t; }
; template <int DK, int MODE> ...
;     ...
;   const int tid = get_tid(), lane = tid & 63, wave = __builtin_amdgcn_readfirstlane(tid >> 6), l32 = lane & 31, h = lane >> 5;
;   const int tq0 = qb * 128 + 32 * wave;
;   const int qpos = tq0 + l32;
;   bf16x8 qf[NKS];
;   {
;     const bf16_t* qp = Q + (size_t)qpos * DK + h * 8;
; #pragma unroll
;     for (int ks = 0; ks < NKS; ++ks) qf[ks] = *(const bf16x8*)(qp + ks * 16);
; #pragma unroll
;     for (int ks = 0; ks < NKS; ++ks) asm volatile("" : "+v"(qf[ks]));
;   }
;   float Fref = 0.f;
;   if (MODE == 1) Fref = F[qb * 128];
;   f32x16 o0, o1;
; #pragma unroll
;   for (int e = 0; e < 16; ++e) { o0[e] = 0.f; o1[e] = 0.f; }
;   float m = -1e30f, lsum = 0.f, R = 1.f;
;   u32x4 rk[NKL], rv[2];
;   float rf = 0.f;
;   auto gload = [&](int jt) {
; #pragma unroll
;     for (int i = 0; i < NKL; ++i) {
;       const int id = tid + 256 * i, row = id / KCH, ch = id % KCH;
;       rk[i] = *(const u32x4*)(K + (size_t)(jt * 64 + row) * DK + ch * 8);
;     }
; #pragma unroll
;     for (int i = 0; i < 2; ++i) {
;       const int id = tid + 256 * i, row = id >> 3, ch = id & 7;
;       rv[i] = *(const u32x4*)(Vt + (size_t)row * Skv + jt * 64 + ch * 8);
;     }
;     if (MODE == 1) rf = F[jt * 64 + (tid & 63)];
;   };
;     ...
;   gload(ASC ? start : ntiles - 1);
;   swrite(0);
;   __syncthreads();
.LBB0_522:
	s_and_b64 s[0:1], s[56:57], exec
	s_cselect_b32 s0, s63, s64
	s_and_b64 vcc, exec, s[48:49]
	s_mov_b64 s[4:5], -1
	s_cbranch_vccz .LBB0_541
	s_load_dwordx2 s[20:21], s[18:19], 0x110
	s_load_dwordx4 s[8:11], s[18:19], 0x100
	v_mov_b32_e32 v36, v188
	s_load_dwordx4 s[4:7], s[18:19], 0x90
	v_mov_b32_e32 v161, v1
	s_waitcnt lgkmcnt(0)
	s_add_u32 s12, s8, s52
	s_addc_u32 s13, s9, s53
	s_add_u32 s22, s10, s52
	s_addc_u32 s23, s11, s53
	s_add_u32 s8, s20, s50
	v_readfirstlane_b32 s1, v36
	s_addc_u32 s9, s21, s51
	s_ashr_i32 s1, s1, 1
	s_lshl_b32 s2, s0, 7
	s_andn2_b32 s1, s1, 31
	v_and_b32_e32 v37, 31, v36
	s_add_i32 s1, s1, s2
	v_bfe_u32 v38, v36, 5, 1
	v_or_b32_e32 v152, s1, v37
	s_waitcnt vmcnt(7)
	v_mov_b64_e32 v[2:3], s[12:13]
	v_mad_i64_i32 v[2:3], s[12:13], v152, s78, v[2:3]
	v_lshlrev_b32_e32 v0, 4, v38
	v_lshl_add_u64 v[2:3], v[2:3], 0, v[0:1]
	global_load_dwordx4 v[80:83], v[2:3], off
	global_load_dwordx4 v[128:131], v[2:3], off offset:32
	global_load_dwordx4 v[124:127], v[2:3], off offset:64
	global_load_dwordx4 v[120:123], v[2:3], off offset:96
	global_load_dwordx4 v[116:119], v[2:3], off offset:128
	global_load_dwordx4 v[112:115], v[2:3], off offset:160
	v_mul_hi_i32 v2, v36, s69
	v_lshrrev_b32_e32 v3, 31, v2
	v_ashrrev_i32_e32 v2, 1, v2
	s_waitcnt vmcnt(7)
	v_add_u32_e32 v28, 0x100, v36
	v_add_u32_e32 v39, v2, v3
	v_mul_hi_i32 v6, v28, s69
	v_mul_lo_u32 v2, v39, 12
	v_lshrrev_b32_e32 v7, 31, v6
	v_ashrrev_i32_e32 v6, 1, v6
	v_add_u32_e32 v12, 0x200, v36
	v_sub_u32_e32 v40, v36, v2
	v_add_u32_e32 v41, v6, v7
	v_mul_hi_i32 v13, v12, s69
	v_lshlrev_b32_e32 v154, 3, v40
	v_mul_lo_u32 v6, v41, 12
	v_lshrrev_b32_e32 v18, 31, v13
	v_ashrrev_i32_e32 v13, 1, v13
	v_mov_b64_e32 v[10:11], s[22:23]
	v_ashrrev_i32_e32 v155, 31, v154
	v_sub_u32_e32 v42, v28, v6
	v_add_u32_e32 v43, v13, v18
	v_mad_i64_i32 v[2:3], s[12:13], v39, s78, v[10:11]
	v_lshlrev_b64 v[14:15], 1, v[154:155]
	v_lshlrev_b32_e32 v156, 3, v42
	v_mul_lo_u32 v13, v43, 12
	v_lshl_add_u64 v[2:3], v[2:3], 0, v[14:15]
	v_ashrrev_i32_e32 v157, 31, v156
	v_sub_u32_e32 v44, v12, v13
	v_ashrrev_i32_e32 v22, 3, v36
	v_mad_i64_i32 v[6:7], s[12:13], v41, s78, v[10:11]
	v_lshlrev_b64 v[16:17], 1, v[156:157]
	v_lshlrev_b32_e32 v158, 3, v44
	v_ashrrev_i32_e32 v23, 31, v22
	v_lshl_add_u64 v[6:7], v[6:7], 0, v[16:17]
	v_ashrrev_i32_e32 v159, 31, v158
	v_lshlrev_b64 v[20:21], 14, v[22:23]
	v_lshlrev_b32_e32 v23, 3, v36
	s_waitcnt vmcnt(6)
	v_ashrrev_i32_e32 v32, 3, v28
	v_mad_i64_i32 v[10:11], s[12:13], v43, s78, v[10:11]
	v_lshlrev_b64 v[18:19], 1, v[158:159]
	v_and_b32_e32 v23, 56, v23
	v_ashrrev_i32_e32 v33, 31, v32
	v_lshl_add_u64 v[10:11], v[10:11], 0, v[18:19]
	v_lshl_add_u64 v[24:25], s[8:9], 0, v[20:21]
	v_lshlrev_b32_e32 v160, 1, v23
	v_lshlrev_b64 v[34:35], 14, v[32:33]
	v_lshl_add_u64 v[24:25], v[24:25], 0, v[160:161]
	v_lshl_add_u64 v[28:29], s[8:9], 0, v[34:35]
	v_lshl_add_u64 v[28:29], v[28:29], 0, v[160:161]
	v_mul_lo_u32 v159, v39, s70
	v_lshlrev_b32_e32 v23, 4, v40
	v_lshl_add_u32 v23, v159, 1, v23
	v_mul_lo_u32 v161, v41, s70
	s_or_b32 s8, s1, 31
	s_movk_i32 s9, 0xd0
	s_or_b32 s2, s2, 64
	v_mad_u32_u24 v175, v37, s9, v0
	s_add_u32 s9, s20, s44
	v_mul_lo_u32 v172, v43, s70
	v_lshlrev_b32_e32 v0, 6, v37
	s_addc_u32 s13, s21, s45
	v_mul_lo_u32 v173, v22, s33
	v_sub_u32_e32 v157, v175, v0
	global_load_dwordx4 v[2:5], v[2:3], off
	s_add_u32 s12, s9, 0x80
	global_load_dwordx4 v[6:9], v[6:7], off
	v_lshlrev_b32_e32 v0, 4, v36
	global_load_dwordx4 v[10:13], v[10:11], off
	v_mul_lo_u32 v174, v32, s33
	global_load_dwordx4 v[24:27], v[24:25], off
	s_addc_u32 s13, s13, 0
	global_load_dwordx4 v[28:31], v[28:29], off
	v_and_b32_e32 v0, 0x70, v0
	v_or_b32_e32 v34, v34, v0
	v_or_b32_e32 v20, v20, v0
	s_add_u32 s10, s10, 0x3000
	v_lshl_add_u64 v[162:163], s[12:13], 0, v[34:35]
	v_lshl_add_u64 v[164:165], s[12:13], 0, v[20:21]
	s_addc_u32 s11, s11, 0
	v_lshlrev_b32_e32 v149, 2, v38
	v_mov_b32_e32 v0, v1
	v_ashrrev_i32_e32 v153, 31, v152
	s_mov_b32 s9, 0
	v_mov_b32_e32 v155, 0xf149f2ca
	v_mov_b32_e32 v151, 0
	s_waitcnt vmcnt(4)
	ds_write_b128 v23, v[2:5]
	v_lshlrev_b32_e32 v2, 4, v42
	v_lshl_add_u32 v2, v161, 1, v2
	s_waitcnt vmcnt(3)
	ds_write_b128 v2, v[6:9]
	v_lshlrev_b32_e32 v2, 4, v44
	v_lshl_add_u32 v2, v172, 1, v2
	s_waitcnt vmcnt(2)
	ds_write_b128 v2, v[10:13]
	v_lshl_add_u32 v2, v173, 1, v160
	s_waitcnt vmcnt(1)
	ds_write_b128 v2, v[24:27] offset:26624
	v_lshl_add_u32 v2, v174, 1, v160
	s_waitcnt vmcnt(0)
	ds_write_b128 v2, v[28:31] offset:26624
	v_mad_i64_i32 v[2:3], s[12:13], v43, s78, v[18:19]
	v_lshl_add_u64 v[166:167], s[10:11], 0, v[2:3]
	v_mad_i64_i32 v[2:3], s[12:13], v41, s78, v[16:17]
	v_lshl_add_u64 v[168:169], s[10:11], 0, v[2:3]
	v_mad_i64_i32 v[2:3], s[12:13], v39, s78, v[14:15]
	v_mov_b32_e32 v14, v1
	v_mov_b32_e32 v15, v1
	v_lshl_add_u64 v[170:171], s[10:11], 0, v[2:3]
	v_mov_b32_e32 v2, v1
	v_mov_b32_e32 v3, v1
	v_mov_b32_e32 v4, v1
	v_mov_b32_e32 v5, v1
	v_mov_b32_e32 v6, v1
	v_mov_b32_e32 v7, v1
	v_mov_b32_e32 v8, v1
	v_mov_b32_e32 v9, v1
	v_mov_b32_e32 v10, v1
	v_mov_b32_e32 v11, v1
	v_mov_b32_e32 v12, v1
	v_mov_b32_e32 v13, v1
	v_mov_b64_e32 v[30:31], v[14:15]
	v_mov_b64_e32 v[46:47], v[14:15]
	s_mov_b32 s10, 0
	v_mov_b64_e32 v[28:29], v[12:13]
	v_mov_b64_e32 v[26:27], v[10:11]
	v_mov_b64_e32 v[24:25], v[8:9]
	v_mov_b64_e32 v[22:23], v[6:7]
	v_mov_b64_e32 v[20:21], v[4:5]
	v_mov_b64_e32 v[18:19], v[2:3]
	v_mov_b64_e32 v[16:17], v[0:1]
	v_mov_b64_e32 v[44:45], v[12:13]
	v_mov_b64_e32 v[42:43], v[10:11]
	v_mov_b64_e32 v[40:41], v[8:9]
	v_mov_b64_e32 v[38:39], v[6:7]
	v_mov_b64_e32 v[36:37], v[4:5]
	v_mov_b64_e32 v[34:35], v[2:3]
	v_mov_b64_e32 v[32:33], v[0:1]
	s_waitcnt lgkmcnt(0)
	s_barrier
	v_lshlrev_b32_e32 v217, 1, v159
	v_lshl_add_u32 v217, v154, 1, v217
	v_lshlrev_b32_e32 v218, 1, v161
	v_lshl_add_u32 v218, v156, 1, v218
	v_lshlrev_b32_e32 v219, 1, v172
	v_lshl_add_u32 v219, v158, 1, v219
	v_lshl_add_u32 v220, v173, 1, v160
	v_lshl_add_u32 v221, v174, 1, v160
	v_lshl_add_u64 v[166:167], v[166:167], 0, s[46:47]
	v_lshl_add_u64 v[168:169], v[168:169], 0, s[46:47]
	v_lshl_add_u64 v[170:171], v[170:171], 0, s[46:47]
	s_branch .LBB0_526

; #define MFMA(a, b, c) __builtin_amdgcn_mfma_f32_32x32x16_bf16((a), (b), (c), 0, 0, 0)
; template <int DK, int MODE> ...
;     ...
;     const int jt = ASC ? start + it : ntiles - 1 - it;
;     const int cur = it & 1;
;     const bool more = it + 1 < nit;
;     if (more) gload(ASC ? jt + 1 : jt - 1);
;     const int key0 = jt * 64;
;     const bool active = !CAUSAL || (key0 <= tq0 + 31);
;     if (active) {
;       f32x16 s0, s1;
;       const bf16_t* kb = sK + cur * 64 * LDK + l32 * LDK + h * 8;
;       bf16x8 kf0[NKS], kf1[NKS];
; #pragma unroll
;       for (int ks = 0; ks < NKS; ++ks) { kf0[ks] = *(const bf16x8*)(kb + ks * 16); kf1[ks] = *(const bf16x8*)(kb + 32 * LDK + ks * 16); }
;       if (MODE == 1) {
;         const float* fb = sF + cur * 64 + 4 * h;
; #pragma unroll
;         for (int g = 0; g < 4; ++g) {
;           const f32x4 f0 = *(const f32x4*)(fb + 8 * g), f1 = *(const f32x4*)(fb + 32 + 8 * g);
;           s0[4 * g] = f0.x; s0[4 * g + 1] = f0.y; s0[4 * g + 2] = f0.z; s0[4 * g + 3] = f0.w;
;           s1[4 * g] = f1.x; s1[4 * g + 1] = f1.y; s1[4 * g + 2] = f1.z; s1[4 * g + 3] = f1.w;
;         }
;       } else {
; #pragma unroll
;         for (int e = 0; e < 16; ++e) { s0[e] = 0.f; s1[e] = 0.f; }
;       }
;       __builtin_amdgcn_iglp_opt(0);
;       __builtin_amdgcn_s_setprio(1);
; #pragma unroll
;       for (int ks = 0; ks < NKS; ++ks) { s0 = MFMA(kf0[ks], qf[ks], s0); s1 = MFMA(kf1[ks], qf[ks], s1); }
;       __builtin_amdgcn_s_setprio(0);
;       const bf16_t* vb = sV + cur * 64 * 72 + l32 * 72 + h * 8;
;       bf16x8 vf0[4], vf1[4];
; #pragma unroll
;       for (int j = 0; j < 4; ++j) { vf0[j] = *(const bf16x8*)(vb + j * 16); vf1[j] = *(const bf16x8*)(vb + 32 * 72 + j * 16); }
;       __builtin_amdgcn_sched_barrier(0);
;       const bool need_mask = CAUSAL && (key0 + 63 >= tq0);
;       bf16x8 pf[4];
;       if (MODE != 2) {
;         if (need_mask) {
; #pragma unroll
;           for (int e = 0; e < 16; ++e) {
;             const int key = key0 + 8 * (e >> 2) + 4 * h + (e & 3);
;             if (key > qpos) s0[e] = -1e30f;
;             if (key + 32 > qpos) s1[e] = -1e30f;
;           }
.LBB0_526:
	s_and_b32 s11, s10, 1
	s_cmp_gt_i32 s9, s8
	s_cbranch_scc1 .Lmla_inactive
	s_mul_i32 s12, s11, 0x3400
	v_add_u32_e32 v0, s12, v175
	ds_read_b128 v[48:51], v0 offset:6656
	ds_read_b128 v[52:55], v0
	ds_read_b128 v[92:95], v0 offset:32
	ds_read_b128 v[96:99], v0 offset:6688
	ds_read_b128 v[100:103], v0 offset:64
	ds_read_b128 v[104:107], v0 offset:6720
	ds_read_b128 v[108:111], v0 offset:96
	ds_read_b128 v[132:135], v0 offset:6752
	ds_read_b128 v[136:139], v0 offset:128
	ds_read_b128 v[140:143], v0 offset:6784
	ds_read_b128 v[176:179], v0 offset:160
	ds_read_b128 v[180:183], v0 offset:6816
	s_setprio 1
	s_waitcnt lgkmcnt(10)
	v_mfma_f32_32x32x16_bf16 v[64:79], v[52:55], v[80:83], 0
	s_mul_i32 s12, s11, 0x2400
	v_add_u32_e32 v0, s12, v157
	v_mfma_f32_32x32x16_bf16 v[48:63], v[48:51], v[80:83], 0
	global_load_dwordx4 v[88:91], v[170:171], off
	s_waitcnt lgkmcnt(9)
	v_mfma_f32_32x32x16_bf16 v[64:79], v[92:95], v[128:131], v[64:79]
	ds_read_b128 v[92:95], v0 offset:31328
	s_waitcnt lgkmcnt(9)
	v_mfma_f32_32x32x16_bf16 v[48:63], v[96:99], v[128:131], v[48:63]
	global_load_dwordx4 v[84:87], v[168:169], off
	ds_read_b128 v[96:99], v0 offset:26720
	s_waitcnt lgkmcnt(9)
	v_mfma_f32_32x32x16_bf16 v[64:79], v[100:103], v[124:127], v[64:79]
	ds_read_b128 v[100:103], v0 offset:26688
	s_waitcnt lgkmcnt(9)
	v_mfma_f32_32x32x16_bf16 v[48:63], v[104:107], v[124:127], v[48:63]
	global_load_dwordx4 v[10:13], v[166:167], off
	ds_read_b128 v[104:107], v0 offset:31296
	s_waitcnt lgkmcnt(9)
	v_mfma_f32_32x32x16_bf16 v[64:79], v[108:111], v[120:123], v[64:79]
	ds_read_b128 v[108:111], v0 offset:26656
	s_waitcnt lgkmcnt(9)
	v_mfma_f32_32x32x16_bf16 v[48:63], v[132:135], v[120:123], v[48:63]
	global_load_dwordx4 v[6:9], v[164:165], off
	ds_read_b128 v[132:135], v0 offset:31264
	s_waitcnt lgkmcnt(9)
	v_mfma_f32_32x32x16_bf16 v[64:79], v[136:139], v[116:119], v[64:79]
	ds_read_b128 v[136:139], v0 offset:26624
	s_waitcnt lgkmcnt(9)
	v_mfma_f32_32x32x16_bf16 v[48:63], v[140:143], v[116:119], v[48:63]
	s_nop 0
	global_load_dwordx4 v[2:5], v[162:163], off
	ds_read_b128 v[140:143], v0 offset:31232
	s_waitcnt lgkmcnt(9)
	v_mfma_f32_32x32x16_bf16 v[64:79], v[176:179], v[112:115], v[64:79]
	s_waitcnt lgkmcnt(8)
	v_mfma_f32_32x32x16_bf16 v[48:63], v[180:183], v[112:115], v[48:63]
	s_setprio 0
	s_add_i32 s12, s9, 63
	s_cmp_lt_i32 s12, s1
	s_cbranch_scc1 .LBB0_529
	v_add_u32_e32 v0, s9, v149
	v_add_u32_e32 v14, 32, v0
	v_cmp_le_i32_e32 vcc, v14, v152
	v_add_u32_e32 v14, 33, v0
	s_nop 4
	v_cndmask_b32_e32 v48, v198, v48, vcc
	v_cmp_lt_i32_e32 vcc, v0, v152
	s_nop 1
	v_cndmask_b32_e32 v65, v198, v65, vcc
	v_cmp_le_i32_e32 vcc, v0, v152
	s_nop 1
	v_cndmask_b32_e32 v64, v198, v64, vcc
	v_cmp_le_i32_e32 vcc, v14, v152
	v_add_u32_e32 v14, 2, v0
	s_nop 0
	v_cndmask_b32_e32 v49, v198, v49, vcc
	v_cmp_le_i32_e32 vcc, v14, v152
	v_add_u32_e32 v14, 34, v0
	s_nop 0
	v_cndmask_b32_e32 v66, v198, v66, vcc
	v_cmp_le_i32_e32 vcc, v14, v152
	v_add_u32_e32 v14, 3, v0
	s_nop 0
	v_cndmask_b32_e32 v50, v198, v50, vcc
	v_cmp_le_i32_e32 vcc, v14, v152
	v_add_u32_e32 v14, 35, v0
	s_nop 0
	v_cndmask_b32_e32 v67, v198, v67, vcc
	v_cmp_le_i32_e32 vcc, v14, v152
	v_add_u32_e32 v14, 8, v0
	s_nop 0
	v_cndmask_b32_e32 v51, v198, v51, vcc
	v_cmp_le_i32_e32 vcc, v14, v152
	v_add_u32_e32 v14, 40, v0
	s_nop 0
	v_cndmask_b32_e32 v68, v198, v68, vcc
	v_cmp_le_i32_e32 vcc, v14, v152
	v_add_u32_e32 v14, 9, v0
	s_nop 0
	v_cndmask_b32_e32 v52, v198, v52, vcc
	v_cmp_le_i32_e32 vcc, v14, v152
	v_add_u32_e32 v14, 41, v0
	s_nop 0
	v_cndmask_b32_e32 v69, v198, v69, vcc
	v_cmp_le_i32_e32 vcc, v14, v152
	v_add_u32_e32 v14, 10, v0
	s_nop 0
	v_cndmask_b32_e32 v53, v198, v53, vcc
	v_cmp_le_i32_e32 vcc, v14, v152
	v_add_u32_e32 v14, 42, v0
	s_nop 0
	v_cndmask_b32_e32 v70, v198, v70, vcc
	v_cmp_le_i32_e32 vcc, v14, v152
	v_add_u32_e32 v14, 11, v0
	s_nop 0
	v_cndmask_b32_e32 v54, v198, v54, vcc
	v_cmp_le_i32_e32 vcc, v14, v152
	v_add_u32_e32 v14, 43, v0
	s_nop 0
	v_cndmask_b32_e32 v71, v198, v71, vcc
	v_cmp_le_i32_e32 vcc, v14, v152
	v_add_u32_e32 v14, 16, v0
	s_nop 0
	v_cndmask_b32_e32 v55, v198, v55, vcc
	v_cmp_le_i32_e32 vcc, v14, v152
	v_add_u32_e32 v14, 48, v0
	s_nop 0
	v_cndmask_b32_e32 v72, v198, v72, vcc
	v_cmp_le_i32_e32 vcc, v14, v152
	v_add_u32_e32 v14, 17, v0
	s_nop 0
	v_cndmask_b32_e32 v56, v198, v56, vcc
	v_cmp_le_i32_e32 vcc, v14, v152
	v_add_u32_e32 v14, 49, v0
	s_nop 0
	v_cndmask_b32_e32 v73, v198, v73, vcc
	v_cmp_le_i32_e32 vcc, v14, v152
	v_add_u32_e32 v14, 18, v0
	s_nop 0
	v_cndmask_b32_e32 v57, v198, v57, vcc
	v_cmp_le_i32_e32 vcc, v14, v152
	v_add_u32_e32 v14, 50, v0
	s_nop 0
	v_cndmask_b32_e32 v74, v198, v74, vcc
	v_cmp_le_i32_e32 vcc, v14, v152
	v_add_u32_e32 v14, 19, v0
	s_nop 0
	v_cndmask_b32_e32 v58, v198, v58, vcc
	v_cmp_le_i32_e32 vcc, v14, v152
	v_add_u32_e32 v14, 51, v0
	s_nop 0
	v_cndmask_b32_e32 v75, v198, v75, vcc
	v_cmp_le_i32_e32 vcc, v14, v152
	v_add_u32_e32 v14, 24, v0
	s_nop 0
	v_cndmask_b32_e32 v59, v198, v59, vcc
	v_cmp_le_i32_e32 vcc, v14, v152
	v_add_u32_e32 v14, 56, v0
	s_nop 0
	v_cndmask_b32_e32 v76, v198, v76, vcc
	v_cmp_le_i32_e32 vcc, v14, v152
	v_add_u32_e32 v14, 25, v0
	s_nop 0
	v_cndmask_b32_e32 v60, v198, v60, vcc
	v_cmp_le_i32_e32 vcc, v14, v152
	v_add_u32_e32 v14, 57, v0
	s_nop 0
	v_cndmask_b32_e32 v77, v198, v77, vcc
	v_cmp_le_i32_e32 vcc, v14, v152
	v_add_u32_e32 v14, 26, v0
	s_nop 0
	v_cndmask_b32_e32 v61, v198, v61, vcc
	v_cmp_le_i32_e32 vcc, v14, v152
	v_add_u32_e32 v14, 58, v0
	s_nop 0
	v_cndmask_b32_e32 v78, v198, v78, vcc
	v_cmp_le_i32_e32 vcc, v14, v152
	v_add_u32_e32 v14, 27, v0
	v_add_u32_e32 v0, 59, v0
	v_cndmask_b32_e32 v62, v198, v62, vcc
	v_cmp_le_i32_e32 vcc, v14, v152
	s_nop 1
	v_cndmask_b32_e32 v79, v198, v79, vcc
	v_cmp_le_i32_e32 vcc, v0, v152
	s_nop 1
	v_cndmask_b32_e32 v63, v198, v63, vcc
